# MLA: next-buffer LDS write address setup moved from the softmax block into the MFMA->VALU wait slot after the last QK MFMA
# baseline (speedup 1.0000x reference)
; #define PIN() do { asm volatile("" ::: "memory"); __builtin_amdgcn_sched_barrier(0); } while (0)
; #define MFMA(a, b, c) __builtin_amdgcn_mfma_f32_32x32x16_bf16((a), (b), (c), 0, 0, 0)
; DI unsigned pk2(float a, float b) { f32x2_t v = {a, b}; bf16x2_t r = __builtin_convertvector(v, bf16x2_t); return __builtin_bit_cast(unsigned, r); }
; #define VLD(dst_, s4_) do { _Pragma("unroll") for (int db = 0; db < 4; ++db) dst_[db].v = *(const bf16x8*)(vbase + db * 32 * VSTR + (s4_) * 32); } while (0)
; template <int DQK, int NM>
; DI void attn_item(const bf16_t* Qb, const bf16_t* Kb, size_t mstride, const bf16_t* VTb,
;                   int q0, int nkt, float cs, bf16_t* Orow  , float lam, float outscale, const float* subw, char* smem) {
;     ...
;     {
;       const f32x2_t cs2 = {cs, cs}, mc2 = {mrun * cs, mrun * cs};
;       f32x2_t ps2 = {0.f, 0.f};
; #pragma unroll
;       for (int kb = 0; kb < 2; ++kb)
; #pragma unroll
;         for (int i = 0; i < 16; i += 2) {
;           f32x2_t t = {sacc[kb][i], sacc[kb][i + 1]};
;           t = t * cs2 - mc2;
;           t.x = __builtin_amdgcn_exp2f(t.x); t.y = __builtin_amdgcn_exp2f(t.y);
;           sacc[kb][i] = t.x; sacc[kb][i + 1] = t.y;
;           ps2 = ps2 + t;
;         }
;       lrun += ps2.x + ps2.y;
;     }
;     const char* vbase = cur + KT_BYTES + l31 * VSTR + hh * 16;
;     {
;       struct VF { bf16x8 v; };
;       VF vfa[4], vfb[4];
;     ...
;       VLD(vfa, 0);
; #pragma unroll
;       for (int s4 = 0; s4 < 4; ++s4) {
;         const int kb = s4 >> 1, sp = s4 & 1;
;         PIN();
;         if (s4 < 3) { if (s4 & 1) VLD(vfa, s4 + 1); else VLD(vfb, s4 + 1); }
;         union { bf16x8 v; unsigned u[4]; } pf;
; #pragma unroll
;         for (int e = 0; e < 4; ++e) pf.u[e] = pk2(sacc[kb][8 * sp + 2 * e], sacc[kb][8 * sp + 2 * e + 1]);
;         PIN();
; #pragma unroll
;         for (int db = 0; db < 4; ++db) { if (s4 & 1) oacc[db] = MFMA(vfb[db].v, pf.v, oacc[db]); else oacc[db] = MFMA(vfa[db].v, pf.v, oacc[db]); }
;         {
;           char* b_ = smem + ((kt + 1) & 1) * BUF;
;           if (s4 == 0) { *(uint4*)(b_ + klo[0]) = kreg0; if (NKC > 2) *(uint4*)(b_ + klo[2]) = kreg2; }
;           if (s4 == 1) { *(uint4*)(b_ + klo[1]) = kreg1; }
;           if (s4 == 2) { *(uint4*)(b_ + vlo0) = vreg0; }
;           if (s4 == 3) { *(uint4*)(b_ + vlo1) = vreg1; }
;         }
;       }
.LBB0_126:
	v_mul_f32_e32 v196, 0x3dd53b95, v218
	v_fma_f32 v80, v80, s26, -v196
	v_fma_f32 v81, v81, s26, -v196
	v_fma_f32 v64, v64, s26, -v196
	v_fma_f32 v65, v65, s26, -v196
	v_exp_f32_e32 v220, v80
	v_exp_f32_e32 v221, v81
	v_fma_f32 v80, v82, s26, -v196
	v_fma_f32 v81, v83, s26, -v196
	v_fma_f32 v82, v88, s26, -v196
	v_fma_f32 v83, v89, s26, -v196
	v_exp_f32_e32 v222, v80
	v_exp_f32_e32 v223, v81
	v_fma_f32 v80, v84, s26, -v196
	v_fma_f32 v81, v85, s26, -v196
	v_exp_f32_e32 v228, v82
	v_exp_f32_e32 v224, v80
	v_exp_f32_e32 v225, v81
	v_fma_f32 v80, v86, s26, -v196
	v_fma_f32 v81, v87, s26, -v196
	v_exp_f32_e32 v229, v83
	v_exp_f32_e32 v226, v80
	v_exp_f32_e32 v227, v81
	v_fma_f32 v82, v90, s26, -v196
	v_fma_f32 v83, v91, s26, -v196
	v_exp_f32_e32 v230, v82
	v_exp_f32_e32 v231, v83
	v_fma_f32 v82, v92, s26, -v196
	v_fma_f32 v83, v93, s26, -v196
	v_exp_f32_e32 v232, v82
	v_exp_f32_e32 v233, v83
	v_fma_f32 v82, v94, s26, -v196
	v_fma_f32 v83, v95, s26, -v196
	v_exp_f32_e32 v234, v82
	v_exp_f32_e32 v235, v83
	v_exp_f32_e32 v236, v64
	v_exp_f32_e32 v237, v65
	v_fma_f32 v64, v66, s26, -v196
	v_fma_f32 v65, v67, s26, -v196
	v_exp_f32_e32 v238, v64
	v_exp_f32_e32 v239, v65
	v_fma_f32 v64, v68, s26, -v196
	v_fma_f32 v65, v69, s26, -v196
	v_exp_f32_e32 v240, v64
	v_exp_f32_e32 v241, v65
	v_fma_f32 v64, v70, s26, -v196
	v_fma_f32 v65, v71, s26, -v196
	v_exp_f32_e32 v242, v64
	v_exp_f32_e32 v243, v65
	v_fma_f32 v66, v72, s26, -v196
	v_fma_f32 v67, v73, s26, -v196
	v_exp_f32_e32 v244, v66
	v_exp_f32_e32 v245, v67
	v_fma_f32 v66, v74, s26, -v196
	v_fma_f32 v67, v75, s26, -v196
	v_exp_f32_e32 v246, v66
	v_exp_f32_e32 v247, v67
	v_fma_f32 v66, v76, s26, -v196
	v_fma_f32 v67, v77, s26, -v196
	v_exp_f32_e32 v248, v66
	v_exp_f32_e32 v249, v67
	v_fma_f32 v66, v78, s26, -v196
	v_fma_f32 v67, v79, s26, -v196
	v_exp_f32_e32 v250, v66
	v_exp_f32_e32 v251, v67
	v_add3_u32 v219, s25, v214, v170
	ds_read_b128 v[64:67], v219 offset:25600
	ds_read_b128 v[68:71], v219 offset:30208
	ds_read_b128 v[72:75], v219 offset:34816
	ds_read_b128 v[76:79], v219 offset:39424
	s_add_i32 s24, s24, 0
	ds_read_b128 v[80:83], v219 offset:25632
	ds_read_b128 v[84:87], v219 offset:30240
	ds_read_b128 v[88:91], v219 offset:34848
	ds_read_b128 v[92:95], v219 offset:39456
	v_add_f32_e32 v203, v220, v221
	v_add_f32_e32 v203, v222, v203
	v_add_f32_e32 v203, v223, v203
	v_add_f32_e32 v203, v224, v203
	v_add_f32_e32 v203, v225, v203
	v_add_f32_e32 v203, v226, v203
	v_add_f32_e32 v203, v227, v203
	v_cvt_pk_bf16_f32 v220, v220, v221
	v_cvt_pk_bf16_f32 v221, v222, v223
	v_cvt_pk_bf16_f32 v222, v224, v225
	v_cvt_pk_bf16_f32 v223, v226, v227
	s_waitcnt lgkmcnt(7)
	s_nop 0
	v_mfma_f32_32x32x16_bf16 v[32:47], v[64:67], v[220:223], v[32:47]
	v_add_f32_e32 v203, v228, v203
	v_add_f32_e32 v203, v229, v203
	s_waitcnt vmcnt(4)
	ds_write_b128 v206, v[158:161]
	s_waitcnt vmcnt(2)
	ds_write_b128 v211, v[162:165]
	s_waitcnt lgkmcnt(8)
	v_mfma_f32_32x32x16_bf16 v[48:63], v[68:71], v[220:223], v[48:63]
	v_add_f32_e32 v203, v230, v203
	v_add_f32_e32 v203, v231, v203
	s_waitcnt lgkmcnt(7)
	v_mfma_f32_32x32x16_bf16 v[16:31], v[72:75], v[220:223], v[16:31]
	v_add_f32_e32 v203, v232, v203
	v_add_f32_e32 v203, v233, v203
	s_waitcnt lgkmcnt(6)
	v_mfma_f32_32x32x16_bf16 v[0:15], v[76:79], v[220:223], v[0:15]
	v_add_f32_e32 v203, v234, v203
	v_add_f32_e32 v203, v235, v203
	ds_read_b128 v[64:67], v219 offset:25664
	ds_read_b128 v[68:71], v219 offset:30272
	ds_read_b128 v[72:75], v219 offset:34880
	ds_read_b128 v[76:79], v219 offset:39488
	v_cvt_pk_bf16_f32 v158, v228, v229
	v_cvt_pk_bf16_f32 v159, v230, v231
	v_cvt_pk_bf16_f32 v160, v232, v233
	v_cvt_pk_bf16_f32 v161, v234, v235
	s_waitcnt lgkmcnt(9)
	s_nop 0
	v_mfma_f32_32x32x16_bf16 v[32:47], v[80:83], v[158:161], v[32:47]
	v_add_f32_e32 v203, v236, v203
	v_add_f32_e32 v203, v237, v203
	v_add_u32_e32 v80, s24, v215
	ds_write_b128 v80, v[154:157]
	s_waitcnt lgkmcnt(9)
	v_mfma_f32_32x32x16_bf16 v[48:63], v[84:87], v[158:161], v[48:63]
	v_add_f32_e32 v203, v238, v203
	v_add_f32_e32 v203, v239, v203
	s_waitcnt lgkmcnt(8)
	v_mfma_f32_32x32x16_bf16 v[16:31], v[88:91], v[158:161], v[16:31]
	v_add_f32_e32 v203, v240, v203
	v_add_f32_e32 v203, v241, v203
	s_waitcnt lgkmcnt(7)
	v_mfma_f32_32x32x16_bf16 v[0:15], v[92:95], v[158:161], v[0:15]
	v_add_f32_e32 v203, v242, v203
	v_add_f32_e32 v203, v243, v203
	ds_read_b128 v[80:83], v219 offset:25696
	ds_read_b128 v[84:87], v219 offset:30304
	ds_read_b128 v[88:91], v219 offset:34912
	ds_read_b128 v[92:95], v219 offset:39520
	v_cvt_pk_bf16_f32 v154, v236, v237
	v_cvt_pk_bf16_f32 v155, v238, v239
	v_cvt_pk_bf16_f32 v156, v240, v241
	v_cvt_pk_bf16_f32 v157, v242, v243
	s_waitcnt lgkmcnt(8)
	s_nop 0
	v_mfma_f32_32x32x16_bf16 v[32:47], v[64:67], v[154:157], v[32:47]
	v_add_f32_e32 v203, v244, v203
	v_add_f32_e32 v203, v245, v203
	v_add_u32_e32 v64, s24, v182
	s_waitcnt vmcnt(1)
	ds_write_b128 v64, v[150:153] offset:25600
	s_waitcnt lgkmcnt(8)
	v_mfma_f32_32x32x16_bf16 v[48:63], v[68:71], v[154:157], v[48:63]
	v_add_f32_e32 v203, v246, v203
	v_add_f32_e32 v203, v247, v203
	s_waitcnt lgkmcnt(7)
	v_mfma_f32_32x32x16_bf16 v[16:31], v[72:75], v[154:157], v[16:31]
	v_add_f32_e32 v203, v248, v203
	v_add_f32_e32 v203, v249, v203
	s_waitcnt lgkmcnt(6)
	v_mfma_f32_32x32x16_bf16 v[0:15], v[76:79], v[154:157], v[0:15]
	v_add_f32_e32 v203, v250, v203
	v_add_f32_e32 v203, v251, v203
	v_cvt_pk_bf16_f32 v64, v244, v245
	v_cvt_pk_bf16_f32 v65, v246, v247
	v_cvt_pk_bf16_f32 v66, v248, v249
	v_cvt_pk_bf16_f32 v67, v250, v251
	s_waitcnt lgkmcnt(4)
	s_nop 0
	v_mfma_f32_32x32x16_bf16 v[32:47], v[80:83], v[64:67], v[32:47]
	v_add_u32_e32 v68, s24, v184
	s_waitcnt vmcnt(0)
	ds_write_b128 v68, v[146:149] offset:25600
	v_add_f32_e32 v185, v185, v203
	s_waitcnt lgkmcnt(4)
	v_mfma_f32_32x32x16_bf16 v[48:63], v[84:87], v[64:67], v[48:63]
	s_waitcnt lgkmcnt(3)
	v_mfma_f32_32x32x16_bf16 v[16:31], v[88:91], v[64:67], v[16:31]
	s_waitcnt lgkmcnt(2)
	v_mfma_f32_32x32x16_bf16 v[0:15], v[92:95], v[64:67], v[0:15]
	s_cmpk_eq_i32 s37, 0x84
	s_waitcnt lgkmcnt(0)
	s_barrier
	s_cbranch_scc1 .LBB0_129
; #define PIN() do { asm volatile("" ::: "memory"); __builtin_amdgcn_sched_barrier(0); } while (0)
; #define GLOAD(kt_) do { const bf16_t* kp_ = Kb + (size_t)(kt_) * 64 * DQK; const bf16_t* vp_ = VTb + (kt_) * 64; \
;     kreg0 = *(const uint4*)(kp_ + kgo[0]); kreg1 = *(const uint4*)(kp_ + kgo[1]); if (NKC > 2) kreg2 = *(const uint4*)(kp_ + kgo[2]); \
;     vreg0 = *(const uint4*)(vp_ + vgo0); vreg1 = *(const uint4*)(vp_ + vgo1); } while (0)
; #define KLD(dst_, s_) do { dst_[0] = *(const bf16x8*)(kbase + (s_) * 32); dst_[1] = *(const bf16x8*)(kbase + 32 * KSTR + (s_) * 32); \
;         dst_[2] = *(const bf16x8*)(kbase + ((s_) + 1) * 32); dst_[3] = *(const bf16x8*)(kbase + 32 * KSTR + ((s_) + 1) * 32); } while (0)
; #define KMM(src_, s_) do { sacc[0] = MFMA(src_[0], qf[s_], sacc[0]); sacc[1] = MFMA(src_[1], qf[s_], sacc[1]); \
;         sacc[0] = MFMA(src_[2], qf[(s_) + 1], sacc[0]); sacc[1] = MFMA(src_[3], qf[(s_) + 1], sacc[1]); } while (0)
; template <int DQK, int NM>
; DI void attn_item(const bf16_t* Qb, const bf16_t* Kb, size_t mstride, const bf16_t* VTb,
;                   int q0, int nkt, float cs, bf16_t* Orow  , float lam, float outscale, const float* subw, char* smem) {
;     ...
;   for (int kt = 0; kt < nkt; ++kt) {
;     const char* cur = smem + (kt & 1) * BUF;
;     GLOAD(kt + 1 < nkt ? kt + 1 : kt);
;     PIN();
;     f32x16 sacc[2];
; #pragma unroll
;     for (int kb = 0; kb < 2; ++kb)
; #pragma unroll
;       for (int i = 0; i < 16; ++i) sacc[kb][i] = 0.f;
;     const char* kbase = cur + (m * 64 + l31) * KSTR + hh * 16;
;     {
;       bf16x8 kfa[4], kfb[4];
;     ...
;       KLD(kfa, 0);
; #pragma unroll
;       for (int g = 0; g < NS / 2; ++g) {
;         PIN();
;         if (g + 1 < NS / 2) { if (g & 1) KLD(kfa, 2 * g + 2); else KLD(kfb, 2 * g + 2); }
;         PIN();
;         if (g & 1) KMM(kfb, 2 * g); else KMM(kfa, 2 * g);
;       }
;     ...
;     }
;     float mx = sacc[0][0];
; #pragma unroll
;     for (int i = 1; i < 16; ++i) mx = fmaxf(mx, sacc[0][i]);
; #pragma unroll
;     for (int i = 0; i < 16; ++i) mx = fmaxf(mx, sacc[1][i]);
;     {
;       const auto rr = __builtin_amdgcn_permlane32_swap(__float_as_uint(mx), __float_as_uint(mx), false, false);
;       mx = fmaxf(__uint_as_float(rr[0]), __uint_as_float(rr[1]));
;     }
;     if (__any((mx - mrun) * cs > 8.f)) {
.LBB0_127:
	v_lshl_add_u64 v[64:65], s[20:21], 0, v[190:191]
	v_lshl_add_u64 v[66:67], s[20:21], 0, v[192:193]
	global_load_dwordx4 v[158:161], v[64:65], off
	global_load_dwordx4 v[154:157], v[66:67], off
	v_lshl_add_u64 v[64:65], s[20:21], 0, v[194:195]
	s_mov_b32 s24, 0xca06000
	v_add_co_u32_e32 v64, vcc, s24, v64
	v_lshl_add_u64 v[66:67], s[20:21], 0, v[186:187]
	s_nop 0
	v_addc_co_u32_e32 v65, vcc, 0, v65, vcc
	global_load_dwordx4 v[162:165], v[64:65], off
	global_load_dwordx4 v[150:153], v[66:67], off
	v_lshl_add_u64 v[64:65], s[20:21], 0, v[188:189]
	global_load_dwordx4 v[146:149], v[64:65], off
	s_and_b32 s24, 1, s37
	s_cselect_b32 s25, 0, 0xac00
	s_add_i32 s25, s25, 0
	v_add3_u32 v196, s25, v217, v170
	ds_read_b128 v[64:67], v196
	ds_read_b128 v[220:223], v196 offset:32
	ds_read_b128 v[68:71], v196 offset:12800
	ds_read_b128 v[224:227], v196 offset:12832
	ds_read_b128 v[228:231], v196 offset:64
	ds_read_b128 v[232:235], v196 offset:96
	ds_read_b128 v[236:239], v196 offset:12864
	ds_read_b128 v[240:243], v196 offset:12896
	s_waitcnt lgkmcnt(7)
	v_mfma_f32_32x32x16_bf16 v[80:95], v[64:67], v[142:145], 0
	s_waitcnt lgkmcnt(5)
	v_mfma_f32_32x32x16_bf16 v[64:79], v[68:71], v[142:145], 0
	v_mfma_f32_32x32x16_bf16 v[80:95], v[220:223], v[136:139], v[80:95]
	s_waitcnt lgkmcnt(4)
	v_mfma_f32_32x32x16_bf16 v[64:79], v[224:227], v[136:139], v[64:79]
	ds_read_b128 v[220:223], v196 offset:128
	ds_read_b128 v[224:227], v196 offset:160
	ds_read_b128 v[244:247], v196 offset:12928
	ds_read_b128 v[248:251], v196 offset:12960
	s_waitcnt lgkmcnt(7)
	v_mfma_f32_32x32x16_bf16 v[80:95], v[228:231], v[132:135], v[80:95]
	s_waitcnt lgkmcnt(5)
	v_mfma_f32_32x32x16_bf16 v[64:79], v[236:239], v[132:135], v[64:79]
	v_mfma_f32_32x32x16_bf16 v[80:95], v[232:235], v[128:131], v[80:95]
	s_waitcnt lgkmcnt(4)
	v_mfma_f32_32x32x16_bf16 v[64:79], v[240:243], v[128:131], v[64:79]
	ds_read_b128 v[228:231], v196 offset:192
	ds_read_b128 v[232:235], v196 offset:224
	ds_read_b128 v[236:239], v196 offset:12992
	ds_read_b128 v[240:243], v196 offset:13024
	s_waitcnt lgkmcnt(7)
	v_mfma_f32_32x32x16_bf16 v[80:95], v[220:223], v[124:127], v[80:95]
	s_waitcnt lgkmcnt(5)
	v_mfma_f32_32x32x16_bf16 v[64:79], v[244:247], v[124:127], v[64:79]
	v_mfma_f32_32x32x16_bf16 v[80:95], v[224:227], v[120:123], v[80:95]
	s_waitcnt lgkmcnt(4)
	v_mfma_f32_32x32x16_bf16 v[64:79], v[248:251], v[120:123], v[64:79]
	ds_read_b128 v[220:223], v196 offset:256
	ds_read_b128 v[224:227], v196 offset:288
	ds_read_b128 v[244:247], v196 offset:13056
	ds_read_b128 v[248:251], v196 offset:13088
	s_waitcnt lgkmcnt(7)
	v_mfma_f32_32x32x16_bf16 v[80:95], v[228:231], v[116:119], v[80:95]
	s_waitcnt lgkmcnt(5)
	v_mfma_f32_32x32x16_bf16 v[64:79], v[236:239], v[116:119], v[64:79]
	v_mfma_f32_32x32x16_bf16 v[80:95], v[232:235], v[112:115], v[80:95]
	s_waitcnt lgkmcnt(4)
	v_mfma_f32_32x32x16_bf16 v[64:79], v[240:243], v[112:115], v[64:79]
	ds_read_b128 v[228:231], v196 offset:320
	ds_read_b128 v[232:235], v196 offset:352
	ds_read_b128 v[236:239], v196 offset:13120
	ds_read_b128 v[240:243], v196 offset:13152
	s_waitcnt lgkmcnt(7)
	v_mfma_f32_32x32x16_bf16 v[80:95], v[220:223], v[108:111], v[80:95]
	s_waitcnt lgkmcnt(5)
	v_mfma_f32_32x32x16_bf16 v[64:79], v[244:247], v[108:111], v[64:79]
	v_mfma_f32_32x32x16_bf16 v[80:95], v[224:227], v[104:107], v[80:95]
	s_waitcnt lgkmcnt(4)
	v_mfma_f32_32x32x16_bf16 v[64:79], v[248:251], v[104:107], v[64:79]
	s_waitcnt lgkmcnt(3)
	v_mfma_f32_32x32x16_bf16 v[80:95], v[228:231], v[100:103], v[80:95]
	s_waitcnt lgkmcnt(2)
	v_mfma_f32_32x32x16_bf16 v[80:95], v[232:235], v[96:99], v[80:95]
	s_waitcnt lgkmcnt(1)
	v_mfma_f32_32x32x16_bf16 v[64:79], v[236:239], v[100:103], v[64:79]
	s_mov_b64 s[34:35], 0x80
	s_add_i32 s37, s37, 1
	v_lshl_add_u64 v[186:187], v[186:187], 0, s[34:35]
	v_lshl_add_u64 v[188:189], v[188:189], 0, s[34:35]
	s_mov_b64 s[34:35], 0x6000
	v_lshl_add_u64 v[190:191], v[190:191], 0, s[34:35]
	v_lshl_add_u64 v[192:193], v[192:193], 0, s[34:35]
	v_lshl_add_u64 v[194:195], v[194:195], 0, s[34:35]
	s_nop 1
	v_max_f32_e32 v196, v81, v81
	v_max_f32_e32 v219, v80, v80
	v_max_f32_e32 v196, v219, v196
	v_max3_f32 v196, v196, v82, v83
	v_max3_f32 v196, v196, v84, v85
	v_max3_f32 v196, v196, v86, v87
	v_max3_f32 v196, v196, v88, v89
	s_waitcnt lgkmcnt(0)
	v_mfma_f32_32x32x16_bf16 v[64:79], v[240:243], v[96:99], v[64:79]
	v_max3_f32 v196, v196, v90, v91
	v_max3_f32 v196, v196, v92, v93
	v_max3_f32 v196, v196, v94, v95
	s_cmp_eq_u32 s24, 1
	s_cselect_b32 s24, 0xac00, 0
	v_add_u32_e32 v206, s24, v197
	v_add_u32_e32 v211, s24, v216
	s_nop 4
	v_max3_f32 v196, v196, v64, v65
	v_max3_f32 v196, v196, v66, v67
	v_max3_f32 v196, v196, v68, v69
	v_max3_f32 v196, v196, v70, v71
	v_max3_f32 v196, v196, v72, v73
	v_max3_f32 v196, v196, v74, v75
	v_max3_f32 v196, v196, v76, v77
	v_max3_f32 v196, v196, v78, v79
	v_mov_b32_e32 v219, v196
	s_nop 1
	v_permlane32_swap_b32_e32 v196, v219
	v_max_f32_e32 v219, v219, v219
	v_max_f32_e32 v196, v196, v196
	v_max_f32_e32 v196, v196, v219
	v_sub_f32_e32 v219, v196, v218
	v_mul_f32_e32 v219, 0x3dd53b95, v219
	v_cmp_lt_f32_e32 vcc, s5, v219
	s_cbranch_vccz .LBB0_126
; template <int DQK, int NM>
; DI void attn_item(const bf16_t* Qb, const bf16_t* Kb, size_t mstride, const bf16_t* VTb,
;                   int q0, int nkt, float cs, bf16_t* Orow  , float lam, float outscale, const float* subw, char* smem) {
;     ...
;     if (__any((mx - mrun) * cs > 8.f)) {
;       const float mnew = fmaxf(mrun, mx);
;       const float alpha = __builtin_amdgcn_exp2f((mrun - mnew) * cs);
;       mrun = mnew;
;       lrun *= alpha;
; #pragma unroll
;       for (int db = 0; db < 4; ++db)
; #pragma unroll
;         for (int i = 0; i < 16; ++i) oacc[db][i] *= alpha;
;     }
	v_max_f32_e32 v196, v196, v196
	v_max_f32_e32 v219, v218, v218
	v_max_f32_e32 v219, v219, v196
	v_sub_f32_e32 v196, v218, v219
	v_mul_f32_e32 v196, 0x3dd53b95, v196
	v_exp_f32_e32 v196, v196
	v_mov_b32_e32 v218, v219
	v_pk_mul_f32 v[46:47], v[46:47], v[196:197] op_sel_hi:[1,0]
	v_pk_mul_f32 v[44:45], v[44:45], v[196:197] op_sel_hi:[1,0]
	v_pk_mul_f32 v[42:43], v[42:43], v[196:197] op_sel_hi:[1,0]
	v_pk_mul_f32 v[40:41], v[40:41], v[196:197] op_sel_hi:[1,0]
	v_pk_mul_f32 v[38:39], v[38:39], v[196:197] op_sel_hi:[1,0]
	v_pk_mul_f32 v[36:37], v[36:37], v[196:197] op_sel_hi:[1,0]
	v_pk_mul_f32 v[34:35], v[34:35], v[196:197] op_sel_hi:[1,0]
	v_pk_mul_f32 v[32:33], v[32:33], v[196:197] op_sel_hi:[1,0]
	v_pk_mul_f32 v[62:63], v[62:63], v[196:197] op_sel_hi:[1,0]
	v_pk_mul_f32 v[60:61], v[60:61], v[196:197] op_sel_hi:[1,0]
	v_pk_mul_f32 v[58:59], v[58:59], v[196:197] op_sel_hi:[1,0]
	v_pk_mul_f32 v[56:57], v[56:57], v[196:197] op_sel_hi:[1,0]
	v_pk_mul_f32 v[54:55], v[54:55], v[196:197] op_sel_hi:[1,0]
	v_pk_mul_f32 v[52:53], v[52:53], v[196:197] op_sel_hi:[1,0]
	v_pk_mul_f32 v[50:51], v[50:51], v[196:197] op_sel_hi:[1,0]
	v_pk_mul_f32 v[48:49], v[48:49], v[196:197] op_sel_hi:[1,0]
	v_pk_mul_f32 v[30:31], v[30:31], v[196:197] op_sel_hi:[1,0]
	v_pk_mul_f32 v[28:29], v[28:29], v[196:197] op_sel_hi:[1,0]
	v_pk_mul_f32 v[26:27], v[26:27], v[196:197] op_sel_hi:[1,0]
	v_pk_mul_f32 v[24:25], v[24:25], v[196:197] op_sel_hi:[1,0]
	v_pk_mul_f32 v[22:23], v[22:23], v[196:197] op_sel_hi:[1,0]
	v_pk_mul_f32 v[20:21], v[20:21], v[196:197] op_sel_hi:[1,0]
	v_pk_mul_f32 v[18:19], v[18:19], v[196:197] op_sel_hi:[1,0]
	v_pk_mul_f32 v[16:17], v[16:17], v[196:197] op_sel_hi:[1,0]
	v_pk_mul_f32 v[14:15], v[14:15], v[196:197] op_sel_hi:[1,0]
	v_pk_mul_f32 v[12:13], v[12:13], v[196:197] op_sel_hi:[1,0]
	v_pk_mul_f32 v[10:11], v[10:11], v[196:197] op_sel_hi:[1,0]
	v_pk_mul_f32 v[8:9], v[8:9], v[196:197] op_sel_hi:[1,0]
	v_pk_mul_f32 v[6:7], v[6:7], v[196:197] op_sel_hi:[1,0]
	v_pk_mul_f32 v[4:5], v[4:5], v[196:197] op_sel_hi:[1,0]
	v_pk_mul_f32 v[2:3], v[2:3], v[196:197] op_sel_hi:[1,0]
	v_pk_mul_f32 v[0:1], v[0:1], v[196:197] op_sel_hi:[1,0]
	v_mul_f32_e32 v185, v185, v196
	s_branch .LBB0_126
